# deferred tail: last 72 sample-attention units (2 per CU) on P3's idle CUs
# baseline (speedup 1.0000x reference)
; __global__ void __launch_bounds__(NTHR, 2) hybrid_fwd(Args args) {
;     ...
;     if ((int)blockIdx.x >= NAS_FREE_FROM && (int)gridDim.x == 256) {
;         Frame F = make_frame(lds);
;         if (F.tid < 64) { unsigned* fl = (unsigned*)(F.ws + WS_CTL) + CW_QREADY; unsigned sp = 0;
;             while (__hip_atomic_load(fl, __ATOMIC_RELAXED, __HIP_MEMORY_SCOPE_AGENT) < (unsigned)G1_SPECIAL) { __builtin_amdgcn_s_sleep(4); if (++sp > (1u << 22)) break; }
;             __builtin_amdgcn_fence(__ATOMIC_ACQUIRE, "agent"); }
;         asm volatile("s_waitcnt vmcnt(0)" ::: "memory"); __syncthreads();
;         for (int u = (int)blockIdx.x - NAS_FREE_FROM; u < NAS_UNITS; u += 256 - NAS_FREE_FROM) attn_sample_head_unit(F, u);
.LBB0_282:
	s_or_b64 exec, exec, s[6:7]
	s_waitcnt vmcnt(0)
	s_cmpk_gt_i32 s2, 0x2df
	s_waitcnt vmcnt(0) lgkmcnt(0)
	s_barrier
	s_cbranch_scc1 .LBB0_311
	s_ashr_i32 s20, s12, 6
	s_lshl_b32 s6, s20, 2
	s_add_i32 s12, s6, 0
	s_sub_i32 s29, s2, 0xe0
	s_movk_i32 s100, 0x20
	s_movk_i32 s101, 0x198
	s_bitcmp1_b32 s98, 6
	s_cbranch_scc0 .Lattn_p1
	s_add_i32 s29, s2, 0xdc
	s_movk_i32 s100, 36
	s_movk_i32 s101, 0x1dc
